# speedup vs baseline: 1.0258x; 1.0258x over previous
; DI float bflo(unsigned v) { return __uint_as_float(v << 16); }
; DI float bfhi(unsigned v) { return __uint_as_float(v & 0xffff0000u); }
; template <int MASK>
; __global__ void __launch_bounds__(256, 2) fwd_megakernel_t(Params p) {
;     ...
;       for (int t = blockIdx.x * 4 + wave; t < T_; t += gridDim.x * 4) {
;         const float rin = rinvx[t];
;         const u16* hr = xb + (size_t)t * 2048;
;         float xn[32];
; #pragma unroll
;         for (int j = 0; j < 2; j++)
; #pragma unroll
;           for (int q = 0; q < 4; q++) {
;             const uint2 a = *(const uint2*)(hr + j * 1024 + lane * 16 + q * 4);
;             const float4 g = *(const float4*)(gffn + j * 1024 + lane * 16 + q * 4);
;             xn[j * 16 + q * 4 + 0] = bflo(a.x) * rin * g.x; xn[j * 16 + q * 4 + 1] = bfhi(a.x) * rin * g.y;
;             xn[j * 16 + q * 4 + 2] = bflo(a.y) * rin * g.z; xn[j * 16 + q * 4 + 3] = bfhi(a.y) * rin * g.w;
;           }
;         const int* ip = pidx + (size_t)t * 128;
;         const float* gp = pgate + (size_t)t * 128;
;         const int idlo = ip[lane], idhi = ip[64 + lane];
;     ...
;           if ((lane & 15) == 0) {
;             const int kk = k + (lane >> 4);
;             const int id = ip[kk];
;             const float av = d * pesu[id];
;             hid[kk] = 0.5f * av * (1.f + erff(av * 0.7071067811865476f)) * gp[kk] * pesv[id];
.LBB0_34:
	v_ashrrev_i32_e32 v29, 31, v28
	v_lshl_add_u64 v[44:45], v[28:29], 2, s[80:81]
	s_waitcnt lgkmcnt(0)
	v_lshlrev_b64 v[0:1], 12, v[28:29]
	global_load_dword v26, v[44:45], off
	v_lshl_add_u64 v[46:47], v[38:39], 0, v[0:1]
	global_load_dwordx4 v[0:3], v[46:47], off offset:16
	global_load_dwordx4 v[6:9], v[46:47], off
	global_load_dwordx4 v[10:13], v[30:31], off offset:48
	global_load_dwordx4 v[14:17], v[30:31], off offset:32
	global_load_dwordx4 v[18:21], v[30:31], off offset:16
	global_load_dwordx4 v[22:25], v[30:31], off
	v_readlane_b32 s12, v255, 49
	v_lshlrev_b64 v[4:5], 9, v[28:29]
	v_readlane_b32 s13, v255, 50
	v_lshlrev_b64 v[48:49], 11, v[28:29]
	v_lshl_add_u64 v[50:51], v[42:43], 0, v[4:5]
	s_mov_b32 s22, 0
	v_mov_b32_e32 v93, v61
	s_waitcnt vmcnt(4)
	v_lshlrev_b32_e32 v27, 16, v6
	v_and_b32_e32 v6, 0xffff0000, v6
	v_mul_f32_e32 v6, v26, v6
	v_mul_f32_e32 v27, v26, v27
	s_waitcnt vmcnt(0)
	v_mul_f32_e32 v53, v6, v23
	v_lshlrev_b32_e32 v6, 16, v7
	v_mul_f32_e32 v6, v26, v6
	v_mul_f32_e32 v63, v6, v24
	v_and_b32_e32 v6, 0xffff0000, v7
	v_mul_f32_e32 v6, v26, v6
	v_mul_f32_e32 v64, v6, v25
	v_lshlrev_b32_e32 v6, 16, v8
	v_mul_f32_e32 v6, v26, v6
	v_mul_f32_e32 v65, v18, v6
	v_and_b32_e32 v6, 0xffff0000, v8
	v_mul_f32_e32 v6, v26, v6
	v_mul_f32_e32 v66, v6, v19
	v_lshlrev_b32_e32 v6, 16, v9
	v_mul_f32_e32 v6, v26, v6
	v_mul_f32_e32 v67, v6, v20
	v_and_b32_e32 v6, 0xffff0000, v9
	v_mul_f32_e32 v6, v26, v6
	v_mul_f32_e32 v68, v6, v21
	v_lshlrev_b32_e32 v6, 16, v0
	v_and_b32_e32 v0, 0xffff0000, v0
	v_mul_f32_e32 v0, v26, v0
	v_mul_f32_e32 v70, v0, v15
	v_lshlrev_b32_e32 v0, 16, v1
	v_mul_f32_e32 v0, v26, v0
	v_mul_f32_e32 v71, v0, v16
	v_and_b32_e32 v0, 0xffff0000, v1
	v_mul_f32_e32 v0, v26, v0
	v_mul_f32_e32 v72, v0, v17
	v_lshlrev_b32_e32 v0, 16, v2
	v_mul_f32_e32 v0, v26, v0
	v_mul_f32_e32 v73, v10, v0
	v_and_b32_e32 v0, 0xffff0000, v2
	v_mul_f32_e32 v0, v26, v0
	v_mul_f32_e32 v74, v0, v11
	v_lshlrev_b32_e32 v0, 16, v3
	v_mul_f32_e32 v0, v26, v0
	v_mul_f32_e32 v75, v0, v12
	v_and_b32_e32 v0, 0xffff0000, v3
	v_mul_f32_e32 v6, v26, v6
	v_mul_f32_e32 v0, v26, v0
	v_mul_f32_e32 v52, v22, v27
	v_mul_f32_e32 v69, v14, v6
	v_mul_f32_e32 v76, v0, v13
	global_load_dwordx4 v[0:3], v[46:47], off offset:2064
	global_load_dwordx4 v[6:9], v[46:47], off offset:2048
	global_load_dwordx4 v[10:13], v[40:41], off offset:48
	global_load_dwordx4 v[14:17], v[40:41], off offset:32
	global_load_dwordx4 v[18:21], v[40:41], off offset:16
	global_load_dwordx4 v[22:25], v[40:41], off
	s_waitcnt vmcnt(4)
	v_lshlrev_b32_e32 v27, 16, v6
	v_and_b32_e32 v6, 0xffff0000, v6
	v_mul_f32_e32 v6, v26, v6
	v_mul_f32_e32 v27, v26, v27
	s_waitcnt vmcnt(0)
	v_mul_f32_e32 v78, v6, v23
	v_lshlrev_b32_e32 v6, 16, v7
	v_mul_f32_e32 v6, v26, v6
	v_mul_f32_e32 v79, v6, v24
	v_and_b32_e32 v6, 0xffff0000, v7
	v_mul_f32_e32 v6, v26, v6
	v_mul_f32_e32 v80, v6, v25
	v_lshlrev_b32_e32 v6, 16, v8
	v_mul_f32_e32 v6, v26, v6
	v_mul_f32_e32 v81, v18, v6
	v_and_b32_e32 v6, 0xffff0000, v8
	v_mul_f32_e32 v6, v26, v6
	v_mul_f32_e32 v82, v6, v19
	v_lshlrev_b32_e32 v6, 16, v9
	v_mul_f32_e32 v6, v26, v6
	v_mul_f32_e32 v83, v6, v20
	v_and_b32_e32 v6, 0xffff0000, v9
	v_mul_f32_e32 v6, v26, v6
	v_mul_f32_e32 v84, v6, v21
	v_lshlrev_b32_e32 v6, 16, v0
	v_and_b32_e32 v0, 0xffff0000, v0
	v_mul_f32_e32 v0, v26, v0
	v_mul_f32_e32 v86, v0, v15
	v_lshlrev_b32_e32 v0, 16, v1
	v_mul_f32_e32 v0, v26, v0
	v_mul_f32_e32 v87, v0, v16
	v_and_b32_e32 v0, 0xffff0000, v1
	v_mul_f32_e32 v0, v26, v0
	v_mul_f32_e32 v88, v0, v17
	v_lshlrev_b32_e32 v0, 16, v2
	v_mul_f32_e32 v0, v26, v0
	v_mul_f32_e32 v89, v10, v0
	v_and_b32_e32 v0, 0xffff0000, v2
	v_mul_f32_e32 v0, v26, v0
	v_mul_f32_e32 v90, v0, v11
	v_lshlrev_b32_e32 v0, 16, v3
	v_mul_f32_e32 v0, v26, v0
	v_mul_f32_e32 v91, v0, v12
	v_and_b32_e32 v0, 0xffff0000, v3
	v_mul_f32_e32 v0, v26, v0
	v_mul_f32_e32 v92, v0, v13
	v_lshl_add_u64 v[0:1], s[12:13], 0, v[4:5]
	v_lshl_add_u64 v[0:1], v[0:1], 0, v[150:151]
	global_load_dword v29, v[0:1], off
	global_load_dword v62, v[0:1], off offset:256
	v_mul_f32_e32 v6, v26, v6
	v_mul_f32_e32 v77, v22, v27
	v_mul_f32_e32 v85, v14, v6
	v_add_co_u32_e32 v216, vcc, 0x800000, v0
	s_nop 1
	v_addc_co_u32_e32 v217, vcc, 0, v1, vcc
	global_load_dword v214, v[216:217], off
	global_load_dword v215, v[216:217], off offset:256
	s_waitcnt vmcnt(2)
	v_mov_b32_e32 v216, v29
	v_ashrrev_i32_e32 v217, 31, v29
	v_mov_b32_e32 v218, v62
	v_ashrrev_i32_e32 v219, 31, v62
	v_lshl_add_u64 v[220:221], v[216:217], 2, s[38:39]
	v_lshl_add_u64 v[222:223], v[216:217], 2, s[96:97]
	v_lshl_add_u64 v[224:225], v[218:219], 2, s[38:39]
	v_lshl_add_u64 v[226:227], v[218:219], 2, s[96:97]
	global_load_dword v210, v[220:221], off
	global_load_dword v212, v[222:223], off
	global_load_dword v211, v[224:225], off
	global_load_dword v213, v[226:227], off
	s_branch .LBB0_37

; template <int MASK>
; __global__ void __launch_bounds__(256, 2) fwd_megakernel_t(Params p) {
;     ...
; #pragma unroll 1
;         for (int k = 0; k < 128; k += 4) {
;           const int idv = (k & 64) ? idhi : idlo;
;           uint4 r[4][2];
; #pragma unroll
;           for (int e = 0; e < 4; e++) {
;             const int id = __builtin_amdgcn_readlane(idv, (k & 63) + e);
;             const unsigned char* ur = peu + (size_t)id * 2048 + lane * 16;
;             r[e][0] = *(const uint4*)ur;
;             r[e][1] = *(const uint4*)(ur + 1024);
;           }
;           float a[4];
; #pragma unroll
;           for (int e = 0; e < 4; e++) {
;             float s0 = 0.f, s1 = 0.f;
;             s0 = dot4_fp8(r[e][0].x, xn[0], xn[1], xn[2], xn[3], s0);
;             s1 = dot4_fp8(r[e][0].y, xn[4], xn[5], xn[6], xn[7], s1);
;             s0 = dot4_fp8(r[e][0].z, xn[8], xn[9], xn[10], xn[11], s0);
;             s1 = dot4_fp8(r[e][0].w, xn[12], xn[13], xn[14], xn[15], s1);
;             s0 = dot4_fp8(r[e][1].x, xn[16], xn[17], xn[18], xn[19], s0);
;             s1 = dot4_fp8(r[e][1].y, xn[20], xn[21], xn[22], xn[23], s1);
;             s0 = dot4_fp8(r[e][1].z, xn[24], xn[25], xn[26], xn[27], s0);
;             s1 = dot4_fp8(r[e][1].w, xn[28], xn[29], xn[30], xn[31], s1);
;             a[e] = s0 + s1;
;           }
.LBB0_37:
	s_cmp_lt_u32 s22, 64
	s_cselect_b64 vcc, -1, 0
	s_waitcnt vmcnt(0)
	v_cndmask_b32_e32 v2, v62, v29, vcc
	s_nop 0
	v_readlane_b32 s12, v2, s22
	s_ashr_i32 s13, s12, 31
	s_lshl_b64 s[12:13], s[12:13], 11
	s_waitcnt lgkmcnt(0)
	v_lshl_add_u64 v[0:1], v[32:33], 0, s[12:13]
	global_load_dwordx4 v[94:97], v[0:1], off
	global_load_dwordx4 v[24:27], v[0:1], off offset:1024
	s_add_i32 s12, s22, 1
	v_readlane_b32 s12, v2, s12
	s_ashr_i32 s13, s12, 31
	s_lshl_b64 s[12:13], s[12:13], 11
	v_lshl_add_u64 v[0:1], v[32:33], 0, s[12:13]
	global_load_dwordx4 v[20:23], v[0:1], off
	global_load_dwordx4 v[16:19], v[0:1], off offset:1024
	s_add_i32 s12, s22, 2
	v_readlane_b32 s12, v2, s12
	s_ashr_i32 s13, s12, 31
	s_lshl_b64 s[12:13], s[12:13], 11
	v_lshl_add_u64 v[0:1], v[32:33], 0, s[12:13]
	global_load_dwordx4 v[12:15], v[0:1], off
	global_load_dwordx4 v[8:11], v[0:1], off offset:1024
	s_add_i32 s12, s22, 3
	v_readlane_b32 s12, v2, s12
	s_ashr_i32 s13, s12, 31
	s_lshl_b64 s[12:13], s[12:13], 11
	v_lshl_add_u64 v[0:1], v[32:33], 0, s[12:13]
	global_load_dwordx4 v[4:7], v[0:1], off
	s_nop 0
	global_load_dwordx4 v[0:3], v[0:1], off offset:1024
	s_waitcnt vmcnt(7)
	v_cvt_pk_f32_fp8_e32 v[98:99], v94
	v_cvt_pk_f32_fp8_sdwa v[100:101], v94 src0_sel:WORD_1
	v_fma_f32 v102, v52, v98, 0
	v_fmac_f32_e32 v102, v53, v99
	v_cvt_pk_f32_fp8_e32 v[98:99], v95
	v_cvt_pk_f32_fp8_sdwa v[94:95], v95 src0_sel:WORD_1
	v_fmac_f32_e32 v102, v63, v100
	v_fmac_f32_e32 v102, v64, v101
	v_fma_f32 v100, v65, v98, 0
	v_fmac_f32_e32 v100, v66, v99
	v_fmac_f32_e32 v100, v67, v94
	v_fmac_f32_e32 v100, v68, v95
	v_cvt_pk_f32_fp8_e32 v[94:95], v96
	v_cvt_pk_f32_fp8_sdwa v[98:99], v96 src0_sel:WORD_1
	v_fmac_f32_e32 v102, v69, v94
	v_fmac_f32_e32 v102, v70, v95
	v_cvt_pk_f32_fp8_e32 v[94:95], v97
	v_fmac_f32_e32 v102, v71, v98
	v_cvt_pk_f32_fp8_sdwa v[96:97], v97 src0_sel:WORD_1
	v_fmac_f32_e32 v102, v72, v99
	v_fmac_f32_e32 v100, v73, v94
	v_fmac_f32_e32 v100, v74, v95
	s_waitcnt vmcnt(6)
	v_cvt_pk_f32_fp8_e32 v[94:95], v24
	v_fmac_f32_e32 v100, v75, v96
	v_fmac_f32_e32 v100, v76, v97
	v_cvt_pk_f32_fp8_sdwa v[96:97], v24 src0_sel:WORD_1
	v_fmac_f32_e32 v102, v77, v94
	v_fmac_f32_e32 v102, v78, v95
	v_cvt_pk_f32_fp8_e32 v[94:95], v25
	v_cvt_pk_f32_fp8_sdwa v[24:25], v25 src0_sel:WORD_1
	v_fmac_f32_e32 v102, v79, v96
	v_fmac_f32_e32 v102, v80, v97
	v_fmac_f32_e32 v100, v81, v94
	v_fmac_f32_e32 v100, v82, v95
	v_fmac_f32_e32 v100, v83, v24
	v_fmac_f32_e32 v100, v84, v25
	v_cvt_pk_f32_fp8_e32 v[24:25], v26
	v_cvt_pk_f32_fp8_sdwa v[94:95], v26 src0_sel:WORD_1
	v_fmac_f32_e32 v102, v85, v24
	v_fmac_f32_e32 v102, v86, v25
	v_cvt_pk_f32_fp8_e32 v[24:25], v27
	v_cvt_pk_f32_fp8_sdwa v[26:27], v27 src0_sel:WORD_1
	v_fmac_f32_e32 v102, v87, v94
	v_fmac_f32_e32 v102, v88, v95
	v_fmac_f32_e32 v100, v89, v24
	v_fmac_f32_e32 v100, v90, v25
	v_fmac_f32_e32 v100, v91, v26
	v_fmac_f32_e32 v100, v92, v27
	s_waitcnt vmcnt(5)
	v_cvt_pk_f32_fp8_e32 v[26:27], v20
	v_cvt_pk_f32_fp8_sdwa v[94:95], v20 src0_sel:WORD_1
	v_add_f32_e32 v24, v102, v100
	v_fma_f32 v25, v52, v26, 0
	v_fmac_f32_e32 v25, v53, v27
	v_cvt_pk_f32_fp8_e32 v[26:27], v21
	v_cvt_pk_f32_fp8_sdwa v[20:21], v21 src0_sel:WORD_1
	v_fmac_f32_e32 v25, v63, v94
	v_fmac_f32_e32 v25, v64, v95
	v_fma_f32 v94, v65, v26, 0
	v_fmac_f32_e32 v94, v66, v27
	v_fmac_f32_e32 v94, v67, v20
	v_fmac_f32_e32 v94, v68, v21
	v_cvt_pk_f32_fp8_e32 v[20:21], v22
	v_cvt_pk_f32_fp8_sdwa v[26:27], v22 src0_sel:WORD_1
	v_fmac_f32_e32 v25, v69, v20
	v_fmac_f32_e32 v25, v70, v21
	v_cvt_pk_f32_fp8_e32 v[20:21], v23
	v_fmac_f32_e32 v25, v71, v26
	v_cvt_pk_f32_fp8_sdwa v[22:23], v23 src0_sel:WORD_1
	v_fmac_f32_e32 v25, v72, v27
	v_fmac_f32_e32 v94, v73, v20
	v_fmac_f32_e32 v94, v74, v21
	s_waitcnt vmcnt(4)
	v_cvt_pk_f32_fp8_e32 v[20:21], v16
	v_fmac_f32_e32 v94, v75, v22
	v_fmac_f32_e32 v94, v76, v23
	v_cvt_pk_f32_fp8_sdwa v[22:23], v16 src0_sel:WORD_1
	v_fmac_f32_e32 v25, v77, v20
	v_fmac_f32_e32 v25, v78, v21
	v_cvt_pk_f32_fp8_e32 v[20:21], v17
	v_cvt_pk_f32_fp8_sdwa v[16:17], v17 src0_sel:WORD_1
	v_fmac_f32_e32 v25, v79, v22
	v_fmac_f32_e32 v25, v80, v23
	v_fmac_f32_e32 v94, v81, v20
	v_fmac_f32_e32 v94, v82, v21
	v_fmac_f32_e32 v94, v83, v16
	v_fmac_f32_e32 v94, v84, v17
	v_cvt_pk_f32_fp8_e32 v[16:17], v18
	v_cvt_pk_f32_fp8_sdwa v[20:21], v18 src0_sel:WORD_1
	v_fmac_f32_e32 v25, v85, v16
	v_fmac_f32_e32 v25, v86, v17
	v_cvt_pk_f32_fp8_e32 v[16:17], v19
	v_cvt_pk_f32_fp8_sdwa v[18:19], v19 src0_sel:WORD_1
	v_fmac_f32_e32 v25, v87, v20
	v_fmac_f32_e32 v25, v88, v21
	v_fmac_f32_e32 v94, v89, v16
	v_fmac_f32_e32 v94, v90, v17
	s_waitcnt vmcnt(3)
	v_cvt_pk_f32_fp8_e32 v[16:17], v12
	v_fmac_f32_e32 v94, v91, v18
	v_fmac_f32_e32 v94, v92, v19
	v_cvt_pk_f32_fp8_sdwa v[18:19], v12 src0_sel:WORD_1
	v_fma_f32 v21, v52, v16, 0
	v_fmac_f32_e32 v21, v53, v17
	v_cvt_pk_f32_fp8_e32 v[16:17], v13
	v_cvt_pk_f32_fp8_sdwa v[12:13], v13 src0_sel:WORD_1
	v_fmac_f32_e32 v21, v63, v18
	v_fmac_f32_e32 v21, v64, v19
	v_fma_f32 v18, v65, v16, 0
	v_fmac_f32_e32 v18, v66, v17
	v_fmac_f32_e32 v18, v67, v12
	v_fmac_f32_e32 v18, v68, v13
	v_cvt_pk_f32_fp8_e32 v[12:13], v14
	v_cvt_pk_f32_fp8_sdwa v[16:17], v14 src0_sel:WORD_1
	v_add_f32_e32 v20, v25, v94
	v_fmac_f32_e32 v21, v69, v12
	v_fmac_f32_e32 v21, v70, v13
	v_cvt_pk_f32_fp8_e32 v[12:13], v15
	v_fmac_f32_e32 v21, v71, v16
	v_cvt_pk_f32_fp8_sdwa v[14:15], v15 src0_sel:WORD_1
	v_fmac_f32_e32 v21, v72, v17
	v_fmac_f32_e32 v18, v73, v12
	v_fmac_f32_e32 v18, v74, v13
	s_waitcnt vmcnt(2)
; template <int MASK>
; __global__ void __launch_bounds__(256, 2) fwd_megakernel_t(Params p) {
;     ...
;           float c2[2], d;
;           {
;             const bool up = lane & 32;
; #pragma unroll
;             for (int i = 0; i < 2; i++) {
;               const float keep = up ? a[2 + i] : a[i], send = up ? a[i] : a[2 + i];
;               c2[i] = keep + __shfl_xor(send, 32);
;             }
;           }
;           {
;             const bool up = lane & 16;
;             const float keep = up ? c2[1] : c2[0], send = up ? c2[0] : c2[1];
;             d = keep + __shfl_xor(send, 16);
;           }
;           d += __shfl_xor(d, 8);
;           d += __shfl_xor(d, 4);
;           d += __shfl_xor(d, 2);
;           d += __shfl_xor(d, 1);
;           if ((lane & 15) == 0) {
;             const int kk = k + (lane >> 4);
;             const int id = ip[kk];
;             const float av = d * pesu[id];
;             hid[kk] = 0.5f * av * (1.f + erff(av * 0.7071067811865476f)) * gp[kk] * pesv[id];
	v_cvt_pk_f32_fp8_e32 v[12:13], v8
	v_fmac_f32_e32 v18, v75, v14
	v_fmac_f32_e32 v18, v76, v15
	v_cvt_pk_f32_fp8_sdwa v[14:15], v8 src0_sel:WORD_1
	v_fmac_f32_e32 v21, v77, v12
	v_fmac_f32_e32 v21, v78, v13
	v_cvt_pk_f32_fp8_e32 v[12:13], v9
	v_cvt_pk_f32_fp8_sdwa v[8:9], v9 src0_sel:WORD_1
	v_fmac_f32_e32 v21, v79, v14
	v_fmac_f32_e32 v21, v80, v15
	v_fmac_f32_e32 v18, v81, v12
	v_fmac_f32_e32 v18, v82, v13
	v_fmac_f32_e32 v18, v83, v8
	v_fmac_f32_e32 v18, v84, v9
	v_cvt_pk_f32_fp8_e32 v[8:9], v10
	v_cvt_pk_f32_fp8_sdwa v[12:13], v10 src0_sel:WORD_1
	v_fmac_f32_e32 v21, v85, v8
	v_fmac_f32_e32 v21, v86, v9
	v_cvt_pk_f32_fp8_e32 v[8:9], v11
	v_cvt_pk_f32_fp8_sdwa v[10:11], v11 src0_sel:WORD_1
	v_fmac_f32_e32 v21, v87, v12
	v_fmac_f32_e32 v21, v88, v13
	v_fmac_f32_e32 v18, v89, v8
	v_fmac_f32_e32 v18, v90, v9
	s_waitcnt vmcnt(1)
	v_cvt_pk_f32_fp8_e32 v[8:9], v4
	v_fmac_f32_e32 v18, v91, v10
	v_fmac_f32_e32 v18, v92, v11
	v_cvt_pk_f32_fp8_sdwa v[10:11], v4 src0_sel:WORD_1
	v_fma_f32 v13, v52, v8, 0
	v_fmac_f32_e32 v13, v53, v9
	v_cvt_pk_f32_fp8_e32 v[8:9], v5
	v_cvt_pk_f32_fp8_sdwa v[4:5], v5 src0_sel:WORD_1
	v_fmac_f32_e32 v13, v63, v10
	v_fmac_f32_e32 v13, v64, v11
	v_fma_f32 v10, v65, v8, 0
	v_fmac_f32_e32 v10, v66, v9
	v_fmac_f32_e32 v10, v67, v4
	v_fmac_f32_e32 v10, v68, v5
	v_cvt_pk_f32_fp8_e32 v[4:5], v6
	v_cvt_pk_f32_fp8_sdwa v[8:9], v6 src0_sel:WORD_1
	v_add_f32_e32 v12, v21, v18
	v_fmac_f32_e32 v13, v69, v4
	v_fmac_f32_e32 v13, v70, v5
	v_cvt_pk_f32_fp8_e32 v[4:5], v7
	v_fmac_f32_e32 v13, v71, v8
	v_cvt_pk_f32_fp8_sdwa v[6:7], v7 src0_sel:WORD_1
	v_fmac_f32_e32 v13, v72, v9
	v_fmac_f32_e32 v10, v73, v4
	v_fmac_f32_e32 v10, v74, v5
	s_waitcnt vmcnt(0)
	v_cvt_pk_f32_fp8_e32 v[4:5], v0
	v_fmac_f32_e32 v10, v75, v6
	v_fmac_f32_e32 v10, v76, v7
	v_cvt_pk_f32_fp8_sdwa v[6:7], v0 src0_sel:WORD_1
	v_fmac_f32_e32 v13, v77, v4
	v_fmac_f32_e32 v13, v78, v5
	v_cvt_pk_f32_fp8_e32 v[4:5], v1
	v_cvt_pk_f32_fp8_sdwa v[0:1], v1 src0_sel:WORD_1
	v_fmac_f32_e32 v13, v79, v6
	v_fmac_f32_e32 v13, v80, v7
	v_fmac_f32_e32 v10, v81, v4
	v_fmac_f32_e32 v10, v82, v5
	v_fmac_f32_e32 v10, v83, v0
	v_fmac_f32_e32 v10, v84, v1
	v_cvt_pk_f32_fp8_e32 v[0:1], v2
	v_cvt_pk_f32_fp8_sdwa v[4:5], v2 src0_sel:WORD_1
	v_fmac_f32_e32 v13, v85, v0
	v_fmac_f32_e32 v13, v86, v1
	v_cvt_pk_f32_fp8_e32 v[0:1], v3
	v_cvt_pk_f32_fp8_sdwa v[2:3], v3 src0_sel:WORD_1
	v_fmac_f32_e32 v13, v87, v4
	v_fmac_f32_e32 v13, v88, v5
	v_fmac_f32_e32 v10, v89, v0
	v_fmac_f32_e32 v10, v90, v1
	v_fmac_f32_e32 v10, v91, v2
	v_cndmask_b32_e64 v2, v24, v12, s[4:5]
	ds_bpermute_b32 v2, v55, v2
	v_fmac_f32_e32 v10, v92, v3
	v_add_f32_e32 v0, v13, v10
	v_cndmask_b32_e64 v1, v12, v24, s[4:5]
	s_waitcnt lgkmcnt(0)
	v_add_f32_e32 v1, v1, v2
	v_cndmask_b32_e64 v2, v0, v20, s[4:5]
	v_cndmask_b32_e64 v0, v20, v0, s[4:5]
	ds_bpermute_b32 v0, v55, v0
	s_waitcnt lgkmcnt(0)
	v_add_f32_e32 v0, v2, v0
	v_cndmask_b32_e64 v2, v0, v1, s[6:7]
	v_cndmask_b32_e64 v0, v1, v0, s[6:7]
	ds_bpermute_b32 v0, v56, v0
	s_waitcnt lgkmcnt(0)
	v_add_f32_e32 v0, v2, v0
	s_nop 1
	v_add_f32_dpp v0, v0, v0 row_ror:8 row_mask:0xf bank_mask:0xf
	s_nop 1
	v_add_f32_dpp v0, v0, v0 row_ror:4 row_mask:0xf bank_mask:0xf
	s_nop 1
	v_add_f32_dpp v0, v0, v0 row_ror:2 row_mask:0xf bank_mask:0xf
	s_nop 1
	v_add_f32_dpp v0, v0, v0 row_ror:1 row_mask:0xf bank_mask:0xf
	s_and_saveexec_b64 s[12:13], s[8:9]
	ds_write_b32 v93, v0
	s_branch .LBB0_36
.LBB0_42:
	s_waitcnt vmcnt(0) lgkmcnt(0)
	v_add_u32_e32 v216, v54, v150
	ds_read_b32 v217, v216
	ds_read_b32 v218, v216 offset:256
	s_waitcnt lgkmcnt(0)
	v_mul_f32_e32 v3, v217, v210
	v_mul_f32_e32 v2, 0x3f3504f3, v3
	v_cmp_nlt_f32_e64 s[20:21], |v2|, 1.0
	s_and_saveexec_b64 s[24:25], s[20:21]
	s_xor_b64 s[20:21], exec, s[24:25]
	s_cbranch_execz .Lp9g_a0
	s_mov_b32 s23, 0x378e98ab
	v_mov_b32_e32 v4, 0xb9c68948
	v_fma_f32 v4, |v2|, s23, v4
	s_mov_b32 s23, 0x3b7cd369
	v_fma_f32 v4, |v2|, v4, s23
	s_mov_b32 s23, 0xbcc618b2
	v_fma_f32 v4, |v2|, v4, s23
	s_mov_b32 s23, 0x3dda74e4
	v_fma_f32 v4, |v2|, v4, s23
	s_mov_b32 s23, 0x3f228afd
	v_fma_f32 v4, |v2|, v4, s23
	s_mov_b32 s23, 0x3e03c728
	v_fma_f32 v4, |v2|, v4, s23
	v_fma_f32 v4, |v2|, v4, |v2|
	v_mul_f32_e32 v5, 0xbfb8aa3b, v4
	v_fma_f32 v6, v4, s41, -v5
	v_rndne_f32_e32 v7, v5
	v_fmac_f32_e32 v6, 0xb2a5705f, v4
	v_sub_f32_e32 v5, v5, v7
	v_add_f32_e32 v5, v5, v6
	v_cvt_i32_f32_e32 v6, v7
	v_exp_f32_e32 v5, v5
	s_mov_b32 s23, 0x42ce8ed0
	v_cmp_nlt_f32_e32 vcc, s23, v4
	s_mov_b32 s23, 0xc2b17218
	v_ldexp_f32 v5, v5, v6
	v_cndmask_b32_e32 v5, 0, v5, vcc
	v_cmp_ngt_f32_e32 vcc, s23, v4
	s_nop 1
	v_cndmask_b32_e32 v4, v195, v5, vcc
	v_sub_f32_e32 v4, 1.0, v4

; template <int MASK>
; __global__ void __launch_bounds__(256, 2) fwd_megakernel_t(Params p) {
;     ...
;           if ((lane & 15) == 0) {
;             const int kk = k + (lane >> 4);
;             const int id = ip[kk];
;             const float av = d * pesu[id];
;             hid[kk] = 0.5f * av * (1.f + erff(av * 0.7071067811865476f)) * gp[kk] * pesv[id];
.Lp9g_b0:
	s_or_b64 exec, exec, s[20:21]
	s_brev_b32 s20, -2
	v_bfi_b32 v2, s20, v4, v2
	v_mul_f32_e32 v3, 0.5, v3
	v_add_f32_e32 v2, 1.0, v2
	v_mul_f32_e32 v4, v3, v2
	v_mul_f32_e32 v2, v214, v4
	v_mul_f32_e32 v0, v212, v2
	ds_write_b32 v216, v0
	v_mul_f32_e32 v3, v218, v211
	v_mul_f32_e32 v2, 0x3f3504f3, v3
	v_cmp_nlt_f32_e64 s[20:21], |v2|, 1.0
	s_and_saveexec_b64 s[24:25], s[20:21]
	s_xor_b64 s[20:21], exec, s[24:25]
	s_cbranch_execz .Lp9g_a1
	s_mov_b32 s23, 0x378e98ab
	v_mov_b32_e32 v4, 0xb9c68948
	v_fma_f32 v4, |v2|, s23, v4
	s_mov_b32 s23, 0x3b7cd369
	v_fma_f32 v4, |v2|, v4, s23
	s_mov_b32 s23, 0xbcc618b2
	v_fma_f32 v4, |v2|, v4, s23
	s_mov_b32 s23, 0x3dda74e4
	v_fma_f32 v4, |v2|, v4, s23
	s_mov_b32 s23, 0x3f228afd
	v_fma_f32 v4, |v2|, v4, s23
	s_mov_b32 s23, 0x3e03c728
	v_fma_f32 v4, |v2|, v4, s23
	v_fma_f32 v4, |v2|, v4, |v2|
	v_mul_f32_e32 v5, 0xbfb8aa3b, v4
	v_fma_f32 v6, v4, s41, -v5
	v_rndne_f32_e32 v7, v5
	v_fmac_f32_e32 v6, 0xb2a5705f, v4
	v_sub_f32_e32 v5, v5, v7
	v_add_f32_e32 v5, v5, v6
	v_cvt_i32_f32_e32 v6, v7
	v_exp_f32_e32 v5, v5
	s_mov_b32 s23, 0x42ce8ed0
	v_cmp_nlt_f32_e32 vcc, s23, v4
	s_mov_b32 s23, 0xc2b17218
	v_ldexp_f32 v5, v5, v6
	v_cndmask_b32_e32 v5, 0, v5, vcc
	v_cmp_ngt_f32_e32 vcc, s23, v4
	s_nop 1
	v_cndmask_b32_e32 v4, v195, v5, vcc
	v_sub_f32_e32 v4, 1.0, v4

; template <int MASK>
; __global__ void __launch_bounds__(256, 2) fwd_megakernel_t(Params p) {
;     ...
;           if ((lane & 15) == 0) {
;             const int kk = k + (lane >> 4);
;             const int id = ip[kk];
;             const float av = d * pesu[id];
;             hid[kk] = 0.5f * av * (1.f + erff(av * 0.7071067811865476f)) * gp[kk] * pesv[id];
;           }
;         }
;         __builtin_amdgcn_wave_barrier();
;         float y[32];
; #pragma unroll
;         for (int i = 0; i < 32; i++) y[i] = 0.f;
; #pragma unroll 1
;         for (int k = 0; k < 128; k += 4) {
;           const int idv = (k & 64) ? idhi : idlo;
.Lp9g_b1:
	s_or_b64 exec, exec, s[20:21]
	s_brev_b32 s20, -2
	v_bfi_b32 v2, s20, v4, v2
	v_mul_f32_e32 v3, 0.5, v3
	v_add_f32_e32 v2, 1.0, v2
	v_mul_f32_e32 v4, v3, v2
	v_mul_f32_e32 v2, v215, v4
	v_mul_f32_e32 v0, v213, v2
	ds_write_b32 v216, v0 offset:256
	v_mov_b32_e32 v4, 0
	s_mov_b32 s12, 0
	v_mov_b32_e32 v63, v54
	v_mov_b32_e32 v5, v4
	v_mov_b32_e32 v6, v4
	v_mov_b32_e32 v7, v4
	v_mov_b32_e32 v8, v4
	v_mov_b32_e32 v9, v4
	v_mov_b32_e32 v10, v4
	v_mov_b32_e32 v11, v4
	v_mov_b32_e32 v12, v4
	v_mov_b32_e32 v13, v4
	v_mov_b32_e32 v14, v4
	v_mov_b32_e32 v15, v4
	v_mov_b32_e32 v16, v4
	v_mov_b32_e32 v17, v4
	v_mov_b32_e32 v18, v4
	v_mov_b32_e32 v19, v4
	v_mov_b32_e32 v20, v4
	v_mov_b32_e32 v21, v4
	v_mov_b32_e32 v22, v4
	v_mov_b32_e32 v23, v4
	v_mov_b32_e32 v24, v4
	v_mov_b32_e32 v25, v4
	v_mov_b32_e32 v26, v4
	v_mov_b32_e32 v27, v4
	v_mov_b32_e32 v50, v4
	v_mov_b32_e32 v51, v4
	v_mov_b32_e32 v52, v4
	v_mov_b32_e32 v53, v4
	v_mov_b32_e32 v2, v4
	v_mov_b32_e32 v3, v4
	v_mov_b32_e32 v0, v4
	s_waitcnt lgkmcnt(0)
	v_mov_b32_e32 v1, v4

; template <class LA>
; DI void gemm_tile(const LA& la, int m0, const u16* __restrict__ Bm, long ldb, int K, f32x16 (&acc)[2][2], char* lds, int tid) {
;     ...
;   const int arow = (wm * 64 + (lane & 31)) * 144 + (lane >> 5) * 16;
;   const int brow = 18432 + (wn * 64 + (lane & 31)) * 144 + (lane >> 5) * 16;
;   char* lds0 = lds;
;   char* lds1 = lds + 36864;
;   __syncthreads();
;   GT_LOAD(p, 0)
;   if (nk > 1) { GT_LOAD(q, 64) }
;   GT_STORE(p, lds0)
;   __syncthreads();
; #pragma unroll 1
;   for (int kt = 0; kt < nk; kt += 2) {
;     if (kt + 2 < nk) { GT_LOAD(p, (kt + 2) * 64) }
; template <int MASK>
; __global__ void __launch_bounds__(256, 2) fwd_megakernel_t(Params p) {
;     ...
;         f32x16 acc[2][2];
;         zero_acc(acc);
;         gemm_tile(LoadPlain{xb, 2048}, m0, w_pq + (size_t)n0 * 2048, 2048, 2048, acc, lds, tid);
.LBB0_278:
	s_or_b64 exec, exec, s[8:9]
	s_lshl_b32 s8, s14, 7
	s_ashr_i32 s9, s8, 31
	s_lshl_b64 s[10:11], s[8:9], 12
	v_add_u32_e32 v0, s6, v130
	v_lshl_add_u64 v[2:3], v[134:135], 0, s[10:11]
	s_waitcnt lgkmcnt(0)
	v_ashrrev_i32_e32 v1, 31, v0
	s_mov_b32 s7, 0x20000
	v_lshlrev_b64 v[20:21], 12, v[0:1]
	v_add_co_u32_e32 v10, vcc, s7, v2
	v_lshl_add_u64 v[0:1], s[82:83], 0, v[20:21]
	v_lshl_add_u64 v[22:23], v[20:21], 0, s[42:43]
	s_mov_b64 s[12:13], 0x40000
	v_addc_co_u32_e32 v11, vcc, 0, v3, vcc
	s_mov_b32 s7, 0x40000
	v_lshl_add_u64 v[4:5], v[0:1], 0, v[150:151]
	v_lshl_add_u64 v[0:1], s[82:83], 0, v[22:23]
	v_lshl_add_u64 v[24:25], v[20:21], 0, s[12:13]
	s_mov_b64 s[12:13], 0x60000
	v_add_co_u32_e32 v12, vcc, s7, v2
	v_lshl_add_u64 v[6:7], v[0:1], 0, v[150:151]
	v_lshl_add_u64 v[0:1], s[82:83], 0, v[24:25]
	v_lshl_add_u64 v[26:27], v[20:21], 0, s[12:13]
	v_addc_co_u32_e32 v13, vcc, 0, v3, vcc
	s_mov_b32 s7, 0x60000
	v_lshl_add_u64 v[8:9], v[0:1], 0, v[150:151]
	v_add_co_u32_e32 v14, vcc, s7, v2
	v_lshl_add_u64 v[0:1], s[82:83], 0, v[26:27]
	s_nop 0
	v_addc_co_u32_e32 v15, vcc, 0, v3, vcc
	v_lshl_add_u64 v[16:17], v[0:1], 0, v[150:151]
	s_barrier
	global_load_dwordx4 v[64:67], v[4:5], off
	global_load_dwordx4 v[68:71], v[6:7], off
	global_load_dwordx4 v[72:75], v[8:9], off
	global_load_dwordx4 v[80:83], v[2:3], off
	global_load_dwordx4 v[88:91], v[10:11], off
	global_load_dwordx4 v[96:99], v[12:13], off
	global_load_dwordx4 v[104:107], v[14:15], off
	global_load_dwordx4 v[76:79], v[16:17], off
	global_load_dwordx4 v[112:115], v[2:3], off offset:128
	global_load_dwordx4 v[84:87], v[4:5], off offset:128
	global_load_dwordx4 v[124:127], v[14:15], off offset:128
	global_load_dwordx4 v[120:123], v[12:13], off offset:128
	global_load_dwordx4 v[116:119], v[10:11], off offset:128
	global_load_dwordx4 v[92:95], v[6:7], off offset:128
	global_load_dwordx4 v[100:103], v[8:9], off offset:128
	global_load_dwordx4 v[108:111], v[16:17], off offset:128
	v_mov_b32_e32 v0, 0
	s_mov_b32 s7, 0
	v_add_u32_e32 v219, v131, v132
	v_mov_b32_e32 v1, v0
	v_mov_b32_e32 v2, v0
	v_mov_b32_e32 v3, v0
	v_mov_b32_e32 v4, v0
	v_mov_b32_e32 v5, v0
	v_mov_b32_e32 v6, v0
	v_mov_b32_e32 v7, v0
	v_mov_b32_e32 v8, v0
	v_mov_b32_e32 v9, v0
	v_mov_b32_e32 v10, v0
	v_mov_b32_e32 v11, v0
	v_mov_b32_e32 v12, v0
	v_mov_b32_e32 v13, v0
	v_mov_b32_e32 v14, v0
	v_mov_b32_e32 v15, v0
	v_mov_b32_e32 v16, v0
	v_mov_b32_e32 v17, v0
	v_mov_b32_e32 v18, v0
	v_mov_b32_e32 v19, v0
	v_lshl_add_u64 v[146:147], s[76:77], 0, v[20:21]
	v_lshl_add_u64 v[156:157], v[144:145], 0, s[10:11]
	v_lshl_add_u64 v[158:159], s[76:77], 0, v[26:27]
	v_lshl_add_u64 v[160:161], s[76:77], 0, v[24:25]
	v_lshl_add_u64 v[162:163], s[76:77], 0, v[22:23]
	v_mov_b32_e32 v20, v0
	v_mov_b32_e32 v21, v0
	v_mov_b32_e32 v22, v0
	v_mov_b32_e32 v23, v0
	v_mov_b32_e32 v24, v0
	v_mov_b32_e32 v25, v0
	v_mov_b32_e32 v26, v0
	v_mov_b32_e32 v27, v0
	v_mov_b32_e32 v28, v0
	v_mov_b32_e32 v29, v0
	v_mov_b32_e32 v30, v0
	v_mov_b32_e32 v31, v0
	v_mov_b32_e32 v32, v0
	v_mov_b32_e32 v33, v0
	v_mov_b32_e32 v34, v0
	v_mov_b32_e32 v35, v0
	v_mov_b32_e32 v36, v0
	v_mov_b32_e32 v37, v0
	v_mov_b32_e32 v38, v0
	v_mov_b32_e32 v39, v0
	v_mov_b32_e32 v40, v0
	v_mov_b32_e32 v41, v0
	v_mov_b32_e32 v42, v0
	v_mov_b32_e32 v43, v0
	v_mov_b32_e32 v44, v0
	v_mov_b32_e32 v45, v0
	v_mov_b32_e32 v46, v0
	v_mov_b32_e32 v47, v0
	v_mov_b32_e32 v48, v0
	v_mov_b32_e32 v49, v0
	v_mov_b32_e32 v50, v0
	v_mov_b32_e32 v51, v0
	v_mov_b32_e32 v52, v0
	v_mov_b32_e32 v53, v0
	v_mov_b32_e32 v54, v0
	v_mov_b32_e32 v55, v0
	v_mov_b32_e32 v56, v0
	v_mov_b32_e32 v57, v0
	v_mov_b32_e32 v58, v0
	v_mov_b32_e32 v59, v0
	v_mov_b32_e32 v60, v0
	v_mov_b32_e32 v61, v0
	v_mov_b32_e32 v62, v0
	v_mov_b32_e32 v63, v0
	s_waitcnt vmcnt(12)
	ds_write_b128 v219, v[80:83] offset:18432
	ds_write_b128 v219, v[64:67]
	s_waitcnt vmcnt(11)
	ds_write_b128 v219, v[88:91] offset:23040
	s_waitcnt vmcnt(10)
	ds_write_b128 v219, v[96:99] offset:27648
	s_waitcnt vmcnt(9)
	ds_write_b128 v219, v[104:107] offset:32256
	ds_write_b128 v219, v[68:71] offset:4608
	ds_write_b128 v219, v[72:75] offset:9216
	s_waitcnt vmcnt(8)
	ds_write_b128 v219, v[76:79] offset:13824
	s_waitcnt lgkmcnt(0)
	s_barrier
	v_lshl_add_u64 v[220:221], v[146:147], 0, v[142:143]
	v_lshl_add_u64 v[222:223], v[156:157], 0, v[142:143]
	v_add_co_u32_e32 v220, vcc, 0x84e0000, v220
	s_nop 1
	v_addc_co_u32_e32 v221, vcc, 0, v221, vcc
	v_add_co_u32_e32 v222, vcc, 0x3a60000, v222
	s_nop 1
	v_addc_co_u32_e32 v223, vcc, 0, v223, vcc
	s_nop 0
	v_readfirstlane_b32 s30, v220
	v_readfirstlane_b32 s31, v221
	v_readfirstlane_b32 s34, v222
	v_readfirstlane_b32 s35, v223
	s_nop 1
	v_subrev_u32_e32 v146, s30, v220
	v_subrev_u32_e32 v200, s34, v222
	v_add_u32_e32 v147, 0x20000, v146
	v_add_u32_e32 v201, 0x20000, v200
	v_add_u32_e32 v172, 0x40000, v146
	v_add_u32_e32 v252, 0x40000, v200
	v_add_u32_e32 v173, 0x60000, v146
	v_add_u32_e32 v253, 0x60000, v200
	ds_read_b128 v[220:223], v136
	ds_read_b128 v[224:227], v136 offset:4608
	ds_read_b128 v[228:231], v137 offset:18432
	ds_read_b128 v[232:235], v137 offset:23040
; template <class LA>
; DI void gemm_tile(const LA& la, int m0, const u16* __restrict__ Bm, long ldb, int K, f32x16 (&acc)[2][2], char* lds, int tid) {
;     ...
;   const int arow = (wm * 64 + (lane & 31)) * 144 + (lane >> 5) * 16;
;   const int brow = 18432 + (wn * 64 + (lane & 31)) * 144 + (lane >> 5) * 16;
;   char* lds0 = lds;
;   char* lds1 = lds + 36864;
;   __syncthreads();
;   GT_LOAD(p, 0)
;   if (nk > 1) { GT_LOAD(q, 64) }
;   GT_STORE(p, lds0)
;   __syncthreads();
; #pragma unroll 1
;   for (int kt = 0; kt < nk; kt += 2) {
;     if (kt + 2 < nk) { GT_LOAD(p, (kt + 2) * 64) }
;     GT_COMPUTE(lds0)
;     if (kt + 1 < nk) { GT_STORE(q, lds1) }
;     __syncthreads();
;     if (kt + 1 >= nk) break;
;     if (kt + 3 < nk) { GT_LOAD(q, (kt + 3) * 64) }
;     GT_COMPUTE(lds1)
;     if (kt + 2 < nk) { GT_STORE(p, lds0) }
;     __syncthreads();
;   }
.Lp7n_loop:
	ds_read_b128 v[236:239], v136 offset:32
	ds_read_b128 v[240:243], v136 offset:4640
	ds_read_b128 v[244:247], v137 offset:18464
	ds_read_b128 v[248:251], v137 offset:23072
	s_waitcnt lgkmcnt(4)
	v_mfma_f32_32x32x16_bf16 v[48:63], v[220:223], v[228:231], v[48:63]
	global_load_dwordx4 v[64:67], v146, s[30:31] offset:256
	v_mfma_f32_32x32x16_bf16 v[32:47], v[220:223], v[232:235], v[32:47]
	global_load_dwordx4 v[68:71], v147, s[30:31] offset:256
	v_mfma_f32_32x32x16_bf16 v[16:31], v[224:227], v[228:231], v[16:31]
	global_load_dwordx4 v[72:75], v172, s[30:31] offset:256
	ds_read_b128 v[164:167], v136 offset:64
	ds_read_b128 v[168:171], v136 offset:4672
	v_mfma_f32_32x32x16_bf16 v[0:15], v[224:227], v[232:235], v[0:15]
	global_load_dwordx4 v[76:79], v173, s[30:31] offset:256
	ds_read_b128 v[156:159], v137 offset:18496
	ds_read_b128 v[160:163], v137 offset:23104
	s_waitcnt lgkmcnt(4)
	v_mfma_f32_32x32x16_bf16 v[48:63], v[236:239], v[244:247], v[48:63]
	global_load_dwordx4 v[80:83], v200, s[34:35] offset:256
	v_mfma_f32_32x32x16_bf16 v[32:47], v[236:239], v[248:251], v[32:47]
	global_load_dwordx4 v[88:91], v201, s[34:35] offset:256
	v_mfma_f32_32x32x16_bf16 v[16:31], v[240:243], v[244:247], v[16:31]
	global_load_dwordx4 v[96:99], v252, s[34:35] offset:256
	ds_read_b128 v[220:223], v136 offset:96
	ds_read_b128 v[224:227], v136 offset:4704
	v_mfma_f32_32x32x16_bf16 v[0:15], v[240:243], v[248:251], v[0:15]
	global_load_dwordx4 v[104:107], v253, s[34:35] offset:256
	ds_read_b128 v[228:231], v137 offset:18528
	ds_read_b128 v[232:235], v137 offset:23136
	s_waitcnt vmcnt(8) lgkmcnt(4)
	v_mfma_f32_32x32x16_bf16 v[48:63], v[164:167], v[156:159], v[48:63]
	ds_write_b128 v219, v[84:87] offset:36864
	ds_write_b128 v219, v[92:95] offset:41472
	ds_write_b128 v219, v[100:103] offset:46080
	v_mfma_f32_32x32x16_bf16 v[32:47], v[164:167], v[160:163], v[32:47]
	ds_write_b128 v219, v[108:111] offset:50688
	ds_write_b128 v219, v[112:115] offset:55296
	ds_write_b128 v219, v[116:119] offset:59904
	v_mfma_f32_32x32x16_bf16 v[16:31], v[168:171], v[156:159], v[16:31]
	ds_write_b128 v219, v[120:123] offset:64512
	ds_write_b128 v218, v[124:127] offset:13824
	v_mfma_f32_32x32x16_bf16 v[0:15], v[168:171], v[160:163], v[0:15]
	s_waitcnt lgkmcnt(0)
	s_barrier
	v_mfma_f32_32x32x16_bf16 v[48:63], v[220:223], v[228:231], v[48:63]
	ds_read_b128 v[236:239], v136 offset:36864
	ds_read_b128 v[240:243], v136 offset:41472
	v_mfma_f32_32x32x16_bf16 v[32:47], v[220:223], v[232:235], v[32:47]
	ds_read_b128 v[244:247], v137 offset:55296
	ds_read_b128 v[248:251], v137 offset:59904
	v_mfma_f32_32x32x16_bf16 v[16:31], v[224:227], v[228:231], v[16:31]
	v_mfma_f32_32x32x16_bf16 v[0:15], v[224:227], v[232:235], v[0:15]
	ds_read_b128 v[164:167], v136 offset:36896
	ds_read_b128 v[168:171], v136 offset:41504
	ds_read_b128 v[156:159], v137 offset:55328
	ds_read_b128 v[160:163], v137 offset:59936
	s_waitcnt lgkmcnt(4)
	v_mfma_f32_32x32x16_bf16 v[48:63], v[236:239], v[244:247], v[48:63]
	global_load_dwordx4 v[84:87], v146, s[30:31] offset:384
	v_mfma_f32_32x32x16_bf16 v[32:47], v[236:239], v[248:251], v[32:47]
	global_load_dwordx4 v[92:95], v147, s[30:31] offset:384
	v_mfma_f32_32x32x16_bf16 v[16:31], v[240:243], v[244:247], v[16:31]
	global_load_dwordx4 v[100:103], v172, s[30:31] offset:384
	ds_read_b128 v[220:223], v136 offset:36928
	ds_read_b128 v[224:227], v136 offset:41536
	v_mfma_f32_32x32x16_bf16 v[0:15], v[240:243], v[248:251], v[0:15]
	global_load_dwordx4 v[108:111], v173, s[30:31] offset:384
	ds_read_b128 v[228:231], v137 offset:55360
	ds_read_b128 v[232:235], v137 offset:59968
	s_waitcnt lgkmcnt(4)
	v_mfma_f32_32x32x16_bf16 v[48:63], v[164:167], v[156:159], v[48:63]
	global_load_dwordx4 v[112:115], v200, s[34:35] offset:384
	v_mfma_f32_32x32x16_bf16 v[32:47], v[164:167], v[160:163], v[32:47]
	global_load_dwordx4 v[116:119], v201, s[34:35] offset:384
	v_mfma_f32_32x32x16_bf16 v[16:31], v[168:171], v[156:159], v[16:31]
	global_load_dwordx4 v[120:123], v252, s[34:35] offset:384
	ds_read_b128 v[236:239], v136 offset:36960
	ds_read_b128 v[240:243], v136 offset:41568
	v_mfma_f32_32x32x16_bf16 v[0:15], v[168:171], v[160:163], v[0:15]
	global_load_dwordx4 v[124:127], v253, s[34:35] offset:384
	ds_read_b128 v[244:247], v137 offset:55392
	ds_read_b128 v[248:251], v137 offset:60000
	s_waitcnt vmcnt(8) lgkmcnt(4)
	v_mfma_f32_32x32x16_bf16 v[48:63], v[220:223], v[228:231], v[48:63]
	ds_write_b128 v219, v[64:67]
	ds_write_b128 v219, v[68:71] offset:4608
	ds_write_b128 v219, v[72:75] offset:9216
	v_mfma_f32_32x32x16_bf16 v[32:47], v[220:223], v[232:235], v[32:47]
	ds_write_b128 v219, v[76:79] offset:13824
	ds_write_b128 v219, v[80:83] offset:18432
	ds_write_b128 v219, v[88:91] offset:23040
	v_mfma_f32_32x32x16_bf16 v[16:31], v[224:227], v[228:231], v[16:31]
	ds_write_b128 v219, v[96:99] offset:27648
	ds_write_b128 v219, v[104:107] offset:32256
	v_mfma_f32_32x32x16_bf16 v[0:15], v[224:227], v[232:235], v[0:15]
	s_waitcnt lgkmcnt(0)
	s_barrier
; template <class LA>
; DI void gemm_tile(const LA& la, int m0, const u16* __restrict__ Bm, long ldb, int K, f32x16 (&acc)[2][2], char* lds, int tid) {
;     ...
;   const int arow = (wm * 64 + (lane & 31)) * 144 + (lane >> 5) * 16;
;   const int brow = 18432 + (wn * 64 + (lane & 31)) * 144 + (lane >> 5) * 16;
;   char* lds0 = lds;
;   char* lds1 = lds + 36864;
;   __syncthreads();
;   GT_LOAD(p, 0)
;   if (nk > 1) { GT_LOAD(q, 64) }
;   GT_STORE(p, lds0)
;   __syncthreads();
; #pragma unroll 1
;   for (int kt = 0; kt < nk; kt += 2) {
;     if (kt + 2 < nk) { GT_LOAD(p, (kt + 2) * 64) }
;     GT_COMPUTE(lds0)
;     if (kt + 1 < nk) { GT_STORE(q, lds1) }
;     __syncthreads();
;     if (kt + 1 >= nk) break;
;     if (kt + 3 < nk) { GT_LOAD(q, (kt + 3) * 64) }
;     GT_COMPUTE(lds1)
;     if (kt + 2 < nk) { GT_STORE(p, lds0) }
;     __syncthreads();
;   }
	v_mfma_f32_32x32x16_bf16 v[48:63], v[236:239], v[244:247], v[48:63]
	ds_read_b128 v[164:167], v136
	ds_read_b128 v[168:171], v136 offset:4608
	v_mfma_f32_32x32x16_bf16 v[32:47], v[236:239], v[248:251], v[32:47]
	ds_read_b128 v[156:159], v137 offset:18432
	ds_read_b128 v[160:163], v137 offset:23040
	v_mfma_f32_32x32x16_bf16 v[16:31], v[240:243], v[244:247], v[16:31]
	v_mfma_f32_32x32x16_bf16 v[0:15], v[240:243], v[248:251], v[0:15]
	ds_read_b128 v[220:223], v136 offset:32
	ds_read_b128 v[224:227], v136 offset:4640
	ds_read_b128 v[228:231], v137 offset:18464
	ds_read_b128 v[232:235], v137 offset:23072
	s_waitcnt lgkmcnt(4)
	v_mfma_f32_32x32x16_bf16 v[48:63], v[164:167], v[156:159], v[48:63]
	global_load_dwordx4 v[64:67], v146, s[30:31] offset:512
	v_mfma_f32_32x32x16_bf16 v[32:47], v[164:167], v[160:163], v[32:47]
	global_load_dwordx4 v[68:71], v147, s[30:31] offset:512
	v_mfma_f32_32x32x16_bf16 v[16:31], v[168:171], v[156:159], v[16:31]
	global_load_dwordx4 v[72:75], v172, s[30:31] offset:512
	ds_read_b128 v[236:239], v136 offset:64
	ds_read_b128 v[240:243], v136 offset:4672
	v_mfma_f32_32x32x16_bf16 v[0:15], v[168:171], v[160:163], v[0:15]
	global_load_dwordx4 v[76:79], v173, s[30:31] offset:512
	ds_read_b128 v[244:247], v137 offset:18496
	ds_read_b128 v[248:251], v137 offset:23104
	s_waitcnt lgkmcnt(4)
	v_mfma_f32_32x32x16_bf16 v[48:63], v[220:223], v[228:231], v[48:63]
	global_load_dwordx4 v[80:83], v200, s[34:35] offset:512
	v_mfma_f32_32x32x16_bf16 v[32:47], v[220:223], v[232:235], v[32:47]
	global_load_dwordx4 v[88:91], v201, s[34:35] offset:512
	v_mfma_f32_32x32x16_bf16 v[16:31], v[224:227], v[228:231], v[16:31]
	global_load_dwordx4 v[96:99], v252, s[34:35] offset:512
	ds_read_b128 v[164:167], v136 offset:96
	ds_read_b128 v[168:171], v136 offset:4704
	v_mfma_f32_32x32x16_bf16 v[0:15], v[224:227], v[232:235], v[0:15]
	global_load_dwordx4 v[104:107], v253, s[34:35] offset:512
	ds_read_b128 v[156:159], v137 offset:18528
	ds_read_b128 v[160:163], v137 offset:23136
	s_waitcnt vmcnt(8) lgkmcnt(4)
	v_mfma_f32_32x32x16_bf16 v[48:63], v[236:239], v[244:247], v[48:63]
	ds_write_b128 v219, v[84:87] offset:36864
	ds_write_b128 v219, v[92:95] offset:41472
	ds_write_b128 v219, v[100:103] offset:46080
	v_mfma_f32_32x32x16_bf16 v[32:47], v[236:239], v[248:251], v[32:47]
	ds_write_b128 v219, v[108:111] offset:50688
	ds_write_b128 v219, v[112:115] offset:55296
	ds_write_b128 v219, v[116:119] offset:59904
	v_mfma_f32_32x32x16_bf16 v[16:31], v[240:243], v[244:247], v[16:31]
	ds_write_b128 v219, v[120:123] offset:64512
	ds_write_b128 v218, v[124:127] offset:13824
	v_mfma_f32_32x32x16_bf16 v[0:15], v[240:243], v[248:251], v[0:15]
	s_waitcnt lgkmcnt(0)
	s_barrier
	v_mfma_f32_32x32x16_bf16 v[48:63], v[164:167], v[156:159], v[48:63]
	ds_read_b128 v[220:223], v136 offset:36864
	ds_read_b128 v[224:227], v136 offset:41472
	v_mfma_f32_32x32x16_bf16 v[32:47], v[164:167], v[160:163], v[32:47]
	ds_read_b128 v[228:231], v137 offset:55296
	ds_read_b128 v[232:235], v137 offset:59904
	v_mfma_f32_32x32x16_bf16 v[16:31], v[168:171], v[156:159], v[16:31]
	v_mfma_f32_32x32x16_bf16 v[0:15], v[168:171], v[160:163], v[0:15]
	ds_read_b128 v[236:239], v136 offset:36896
	ds_read_b128 v[240:243], v136 offset:41504
	ds_read_b128 v[244:247], v137 offset:55328
	ds_read_b128 v[248:251], v137 offset:59936
	s_waitcnt lgkmcnt(4)
	v_mfma_f32_32x32x16_bf16 v[48:63], v[220:223], v[228:231], v[48:63]
	global_load_dwordx4 v[84:87], v146, s[30:31] offset:640
	v_mfma_f32_32x32x16_bf16 v[32:47], v[220:223], v[232:235], v[32:47]
	global_load_dwordx4 v[92:95], v147, s[30:31] offset:640
	v_mfma_f32_32x32x16_bf16 v[16:31], v[224:227], v[228:231], v[16:31]
	global_load_dwordx4 v[100:103], v172, s[30:31] offset:640
	ds_read_b128 v[164:167], v136 offset:36928
	ds_read_b128 v[168:171], v136 offset:41536
	v_mfma_f32_32x32x16_bf16 v[0:15], v[224:227], v[232:235], v[0:15]
	global_load_dwordx4 v[108:111], v173, s[30:31] offset:640
	ds_read_b128 v[156:159], v137 offset:55360
	ds_read_b128 v[160:163], v137 offset:59968
	s_waitcnt lgkmcnt(4)
	v_mfma_f32_32x32x16_bf16 v[48:63], v[236:239], v[244:247], v[48:63]
	global_load_dwordx4 v[112:115], v200, s[34:35] offset:640
	v_mfma_f32_32x32x16_bf16 v[32:47], v[236:239], v[248:251], v[32:47]
	global_load_dwordx4 v[116:119], v201, s[34:35] offset:640
	v_mfma_f32_32x32x16_bf16 v[16:31], v[240:243], v[244:247], v[16:31]
	global_load_dwordx4 v[120:123], v252, s[34:35] offset:640
	ds_read_b128 v[220:223], v136 offset:36960
	ds_read_b128 v[224:227], v136 offset:41568
	v_mfma_f32_32x32x16_bf16 v[0:15], v[240:243], v[248:251], v[0:15]
	global_load_dwordx4 v[124:127], v253, s[34:35] offset:640
	ds_read_b128 v[228:231], v137 offset:55392
	ds_read_b128 v[232:235], v137 offset:60000
	s_waitcnt vmcnt(8) lgkmcnt(4)
	v_mfma_f32_32x32x16_bf16 v[48:63], v[164:167], v[156:159], v[48:63]
	ds_write_b128 v219, v[64:67]
	ds_write_b128 v219, v[68:71] offset:4608
	ds_write_b128 v219, v[72:75] offset:9216
	v_mfma_f32_32x32x16_bf16 v[32:47], v[164:167], v[160:163], v[32:47]
	ds_write_b128 v219, v[76:79] offset:13824
	ds_write_b128 v219, v[80:83] offset:18432
	ds_write_b128 v219, v[88:91] offset:23040
	v_mfma_f32_32x32x16_bf16 v[16:31], v[168:171], v[156:159], v[16:31]
	ds_write_b128 v219, v[96:99] offset:27648
	ds_write_b128 v219, v[104:107] offset:32256
	v_mfma_f32_32x32x16_bf16 v[0:15], v[168:171], v[160:163], v[0:15]
	s_waitcnt lgkmcnt(0)
	s_barrier
; template <class LA>
; DI void gemm_tile(const LA& la, int m0, const u16* __restrict__ Bm, long ldb, int K, f32x16 (&acc)[2][2], char* lds, int tid) {
;     ...
;   const int arow = (wm * 64 + (lane & 31)) * 144 + (lane >> 5) * 16;
;   const int brow = 18432 + (wn * 64 + (lane & 31)) * 144 + (lane >> 5) * 16;
;   char* lds0 = lds;
;   char* lds1 = lds + 36864;
;   __syncthreads();
;   GT_LOAD(p, 0)
;   if (nk > 1) { GT_LOAD(q, 64) }
;   GT_STORE(p, lds0)
;   __syncthreads();
; #pragma unroll 1
;   for (int kt = 0; kt < nk; kt += 2) {
;     if (kt + 2 < nk) { GT_LOAD(p, (kt + 2) * 64) }
;     GT_COMPUTE(lds0)
;     if (kt + 1 < nk) { GT_STORE(q, lds1) }
;     __syncthreads();
;     if (kt + 1 >= nk) break;
;     if (kt + 3 < nk) { GT_LOAD(q, (kt + 3) * 64) }
;     GT_COMPUTE(lds1)
;     if (kt + 2 < nk) { GT_STORE(p, lds0) }
;     __syncthreads();
;   }
	v_mfma_f32_32x32x16_bf16 v[48:63], v[220:223], v[228:231], v[48:63]
	ds_read_b128 v[236:239], v136
	ds_read_b128 v[240:243], v136 offset:4608
	v_mfma_f32_32x32x16_bf16 v[32:47], v[220:223], v[232:235], v[32:47]
	ds_read_b128 v[244:247], v137 offset:18432
	ds_read_b128 v[248:251], v137 offset:23040
	v_mfma_f32_32x32x16_bf16 v[16:31], v[224:227], v[228:231], v[16:31]
	v_mfma_f32_32x32x16_bf16 v[0:15], v[224:227], v[232:235], v[0:15]
	ds_read_b128 v[164:167], v136 offset:32
	ds_read_b128 v[168:171], v136 offset:4640
	ds_read_b128 v[156:159], v137 offset:18464
	ds_read_b128 v[160:163], v137 offset:23072
	s_waitcnt lgkmcnt(4)
	v_mfma_f32_32x32x16_bf16 v[48:63], v[236:239], v[244:247], v[48:63]
	global_load_dwordx4 v[64:67], v146, s[30:31] offset:768
	v_mfma_f32_32x32x16_bf16 v[32:47], v[236:239], v[248:251], v[32:47]
	global_load_dwordx4 v[68:71], v147, s[30:31] offset:768
	v_mfma_f32_32x32x16_bf16 v[16:31], v[240:243], v[244:247], v[16:31]
	global_load_dwordx4 v[72:75], v172, s[30:31] offset:768
	ds_read_b128 v[220:223], v136 offset:64
	ds_read_b128 v[224:227], v136 offset:4672
	v_mfma_f32_32x32x16_bf16 v[0:15], v[240:243], v[248:251], v[0:15]
	global_load_dwordx4 v[76:79], v173, s[30:31] offset:768
	ds_read_b128 v[228:231], v137 offset:18496
	ds_read_b128 v[232:235], v137 offset:23104
	s_waitcnt lgkmcnt(4)
	v_mfma_f32_32x32x16_bf16 v[48:63], v[164:167], v[156:159], v[48:63]
	global_load_dwordx4 v[80:83], v200, s[34:35] offset:768
	v_mfma_f32_32x32x16_bf16 v[32:47], v[164:167], v[160:163], v[32:47]
	global_load_dwordx4 v[88:91], v201, s[34:35] offset:768
	v_mfma_f32_32x32x16_bf16 v[16:31], v[168:171], v[156:159], v[16:31]
	global_load_dwordx4 v[96:99], v252, s[34:35] offset:768
	ds_read_b128 v[236:239], v136 offset:96
	ds_read_b128 v[240:243], v136 offset:4704
	v_mfma_f32_32x32x16_bf16 v[0:15], v[168:171], v[160:163], v[0:15]
	global_load_dwordx4 v[104:107], v253, s[34:35] offset:768
	ds_read_b128 v[244:247], v137 offset:18528
	ds_read_b128 v[248:251], v137 offset:23136
	s_waitcnt vmcnt(8) lgkmcnt(4)
	v_mfma_f32_32x32x16_bf16 v[48:63], v[220:223], v[228:231], v[48:63]
	ds_write_b128 v219, v[84:87] offset:36864
	ds_write_b128 v219, v[92:95] offset:41472
	ds_write_b128 v219, v[100:103] offset:46080
	v_mfma_f32_32x32x16_bf16 v[32:47], v[220:223], v[232:235], v[32:47]
	ds_write_b128 v219, v[108:111] offset:50688
	ds_write_b128 v219, v[112:115] offset:55296
	ds_write_b128 v219, v[116:119] offset:59904
	v_mfma_f32_32x32x16_bf16 v[16:31], v[224:227], v[228:231], v[16:31]
	ds_write_b128 v219, v[120:123] offset:64512
	ds_write_b128 v218, v[124:127] offset:13824
	v_mfma_f32_32x32x16_bf16 v[0:15], v[224:227], v[232:235], v[0:15]
	s_waitcnt lgkmcnt(0)
	s_barrier
	v_mfma_f32_32x32x16_bf16 v[48:63], v[236:239], v[244:247], v[48:63]
	ds_read_b128 v[164:167], v136 offset:36864
	ds_read_b128 v[168:171], v136 offset:41472
	v_mfma_f32_32x32x16_bf16 v[32:47], v[236:239], v[248:251], v[32:47]
	ds_read_b128 v[156:159], v137 offset:55296
	ds_read_b128 v[160:163], v137 offset:59904
	v_mfma_f32_32x32x16_bf16 v[16:31], v[240:243], v[244:247], v[16:31]
	v_mfma_f32_32x32x16_bf16 v[0:15], v[240:243], v[248:251], v[0:15]
	ds_read_b128 v[220:223], v136 offset:36896
	ds_read_b128 v[224:227], v136 offset:41504
	ds_read_b128 v[228:231], v137 offset:55328
	ds_read_b128 v[232:235], v137 offset:59936
	s_waitcnt lgkmcnt(4)
	v_mfma_f32_32x32x16_bf16 v[48:63], v[164:167], v[156:159], v[48:63]
	global_load_dwordx4 v[84:87], v146, s[30:31] offset:896
	v_mfma_f32_32x32x16_bf16 v[32:47], v[164:167], v[160:163], v[32:47]
	global_load_dwordx4 v[92:95], v147, s[30:31] offset:896
	v_mfma_f32_32x32x16_bf16 v[16:31], v[168:171], v[156:159], v[16:31]
	global_load_dwordx4 v[100:103], v172, s[30:31] offset:896
	ds_read_b128 v[236:239], v136 offset:36928
	ds_read_b128 v[240:243], v136 offset:41536
	v_mfma_f32_32x32x16_bf16 v[0:15], v[168:171], v[160:163], v[0:15]
	global_load_dwordx4 v[108:111], v173, s[30:31] offset:896
	ds_read_b128 v[244:247], v137 offset:55360
	ds_read_b128 v[248:251], v137 offset:59968
	s_waitcnt lgkmcnt(4)
	v_mfma_f32_32x32x16_bf16 v[48:63], v[220:223], v[228:231], v[48:63]
	global_load_dwordx4 v[112:115], v200, s[34:35] offset:896
	v_mfma_f32_32x32x16_bf16 v[32:47], v[220:223], v[232:235], v[32:47]
	global_load_dwordx4 v[116:119], v201, s[34:35] offset:896
	v_mfma_f32_32x32x16_bf16 v[16:31], v[224:227], v[228:231], v[16:31]
	global_load_dwordx4 v[120:123], v252, s[34:35] offset:896
	ds_read_b128 v[164:167], v136 offset:36960
	ds_read_b128 v[168:171], v136 offset:41568
	v_mfma_f32_32x32x16_bf16 v[0:15], v[224:227], v[232:235], v[0:15]
	global_load_dwordx4 v[124:127], v253, s[34:35] offset:896
	ds_read_b128 v[156:159], v137 offset:55392
	ds_read_b128 v[160:163], v137 offset:60000
	s_waitcnt vmcnt(8) lgkmcnt(4)
	v_mfma_f32_32x32x16_bf16 v[48:63], v[236:239], v[244:247], v[48:63]
	ds_write_b128 v219, v[64:67]
	ds_write_b128 v219, v[68:71] offset:4608
	ds_write_b128 v219, v[72:75] offset:9216
	v_mfma_f32_32x32x16_bf16 v[32:47], v[236:239], v[248:251], v[32:47]
	ds_write_b128 v219, v[76:79] offset:13824
	ds_write_b128 v219, v[80:83] offset:18432
	ds_write_b128 v219, v[88:91] offset:23040
	v_mfma_f32_32x32x16_bf16 v[16:31], v[240:243], v[244:247], v[16:31]
	ds_write_b128 v219, v[96:99] offset:27648
	ds_write_b128 v219, v[104:107] offset:32256
	v_mfma_f32_32x32x16_bf16 v[0:15], v[240:243], v[248:251], v[0:15]
	s_waitcnt lgkmcnt(0)
	s_barrier
	v_mfma_f32_32x32x16_bf16 v[48:63], v[164:167], v[156:159], v[48:63]
	ds_read_b128 v[220:223], v136
	ds_read_b128 v[224:227], v136 offset:4608
	v_mfma_f32_32x32x16_bf16 v[32:47], v[164:167], v[160:163], v[32:47]
	ds_read_b128 v[228:231], v137 offset:18432
	ds_read_b128 v[232:235], v137 offset:23040
	v_mfma_f32_32x32x16_bf16 v[16:31], v[168:171], v[156:159], v[16:31]
	v_mfma_f32_32x32x16_bf16 v[0:15], v[168:171], v[160:163], v[0:15]
	s_add_u32 s30, s30, 0x300
	s_addc_u32 s31, s31, 0
	s_add_u32 s34, s34, 0x300
	s_addc_u32 s35, s35, 0
	s_add_i32 s7, s7, 6
	s_cmp_lt_u32 s7, 30
	s_cbranch_scc1 .Lp7n_loop
	s_branch .LBB0_280

; template <class LA>
; DI void gemm_tile(const LA& la, int m0, const u16* __restrict__ Bm, long ldb, int K, f32x16 (&acc)[2][2], char* lds, int tid) {
;     ...
;   const int arow = (wm * 64 + (lane & 31)) * 144 + (lane >> 5) * 16;
;   const int brow = 18432 + (wn * 64 + (lane & 31)) * 144 + (lane >> 5) * 16;
;   char* lds0 = lds;
;   char* lds1 = lds + 36864;
;   __syncthreads();
;   GT_LOAD(p, 0)
;   if (nk > 1) { GT_LOAD(q, 64) }
;   GT_STORE(p, lds0)
;   __syncthreads();
; #pragma unroll 1
;   for (int kt = 0; kt < nk; kt += 2) {
;     if (kt + 2 < nk) { GT_LOAD(p, (kt + 2) * 64) }
; template <int MASK>
; __global__ void __launch_bounds__(256, 2) fwd_megakernel_t(Params p) {
;     ...
;         f32x16 acc[2][2];
;         zero_acc(acc);
;         gemm_tile(LoadPlain{merged, 2048}, m0, w_out + (size_t)n0 * 2048, 2048, 2048, acc, lds, tid);
.LBB0_300:
	s_lshl_b32 s8, s17, 7
	s_lshl_b32 s6, s16, 7
	s_ashr_i32 s9, s8, 31
	s_lshl_b64 s[10:11], s[8:9], 12
	v_add_u32_e32 v0, s6, v128
	v_lshl_add_u64 v[2:3], v[132:133], 0, s[10:11]
	s_waitcnt lgkmcnt(0)
	v_ashrrev_i32_e32 v1, 31, v0
	s_mov_b32 s7, 0x20000
	v_lshlrev_b64 v[20:21], 12, v[0:1]
	v_add_co_u32_e32 v10, vcc, s7, v2
	v_lshl_add_u64 v[0:1], s[92:93], 0, v[20:21]
	v_lshl_add_u64 v[22:23], v[20:21], 0, s[42:43]
	s_mov_b64 s[12:13], 0x40000
	v_addc_co_u32_e32 v11, vcc, 0, v3, vcc
	s_mov_b32 s7, 0x40000
	v_lshl_add_u64 v[4:5], v[0:1], 0, v[150:151]
	v_lshl_add_u64 v[0:1], s[92:93], 0, v[22:23]
	v_lshl_add_u64 v[24:25], v[20:21], 0, s[12:13]
	v_add_co_u32_e32 v12, vcc, s7, v2
	s_mov_b64 s[12:13], 0x60000
	v_lshl_add_u64 v[6:7], v[0:1], 0, v[150:151]
	v_lshl_add_u64 v[0:1], s[92:93], 0, v[24:25]
	v_addc_co_u32_e32 v13, vcc, 0, v3, vcc
	s_mov_b32 s7, 0x60000
	v_lshl_add_u64 v[26:27], v[20:21], 0, s[12:13]
	v_lshl_add_u64 v[8:9], v[0:1], 0, v[150:151]
	v_add_co_u32_e32 v14, vcc, s7, v2
	v_lshl_add_u64 v[0:1], s[92:93], 0, v[26:27]
	s_nop 0
	v_addc_co_u32_e32 v15, vcc, 0, v3, vcc
	v_lshl_add_u64 v[16:17], v[0:1], 0, v[150:151]
	s_waitcnt vmcnt(63) expcnt(7) lgkmcnt(15)
	s_barrier
	global_load_dwordx4 v[64:67], v[4:5], off
	global_load_dwordx4 v[68:71], v[6:7], off
	global_load_dwordx4 v[72:75], v[8:9], off
	global_load_dwordx4 v[80:83], v[2:3], off
	global_load_dwordx4 v[88:91], v[10:11], off
	global_load_dwordx4 v[96:99], v[12:13], off
	global_load_dwordx4 v[104:107], v[14:15], off
	global_load_dwordx4 v[76:79], v[16:17], off
	global_load_dwordx4 v[112:115], v[2:3], off offset:128
	global_load_dwordx4 v[124:127], v[14:15], off offset:128
	global_load_dwordx4 v[120:123], v[12:13], off offset:128
	global_load_dwordx4 v[116:119], v[10:11], off offset:128
	global_load_dwordx4 v[84:87], v[4:5], off offset:128
	global_load_dwordx4 v[92:95], v[6:7], off offset:128
	global_load_dwordx4 v[100:103], v[8:9], off offset:128
	global_load_dwordx4 v[108:111], v[16:17], off offset:128
	v_mov_b32_e32 v0, 0
	s_mov_b32 s7, 0
	v_add_u32_e32 v173, v129, v130
	v_mov_b32_e32 v1, v0
	v_mov_b32_e32 v2, v0
	v_mov_b32_e32 v3, v0
	v_mov_b32_e32 v4, v0
	v_mov_b32_e32 v5, v0
	v_mov_b32_e32 v6, v0
	v_mov_b32_e32 v7, v0
	v_mov_b32_e32 v8, v0
	v_mov_b32_e32 v9, v0
	v_mov_b32_e32 v10, v0
	v_mov_b32_e32 v11, v0
	v_mov_b32_e32 v12, v0
	v_mov_b32_e32 v13, v0
	v_mov_b32_e32 v14, v0
	v_mov_b32_e32 v15, v0
	v_mov_b32_e32 v16, v0
	v_mov_b32_e32 v17, v0
	v_mov_b32_e32 v18, v0
	v_mov_b32_e32 v19, v0
	s_waitcnt vmcnt(32)
	v_lshl_add_u64 v[144:145], v[142:143], 0, s[10:11]
	v_lshl_add_u64 v[146:147], s[76:77], 0, v[20:21]
	v_lshl_add_u64 v[156:157], s[76:77], 0, v[26:27]
	v_lshl_add_u64 v[158:159], s[76:77], 0, v[24:25]
	v_lshl_add_u64 v[160:161], s[76:77], 0, v[22:23]
	v_mov_b32_e32 v20, v0
	v_mov_b32_e32 v21, v0
	v_mov_b32_e32 v22, v0
	v_mov_b32_e32 v23, v0
	v_mov_b32_e32 v24, v0
	v_mov_b32_e32 v25, v0
	v_mov_b32_e32 v26, v0
	v_mov_b32_e32 v27, v0
	v_mov_b32_e32 v28, v0
	v_mov_b32_e32 v29, v0
	v_mov_b32_e32 v30, v0
	v_mov_b32_e32 v31, v0
	s_waitcnt vmcnt(16)
	v_mov_b32_e32 v32, v0
	v_mov_b32_e32 v33, v0
	v_mov_b32_e32 v34, v0
	v_mov_b32_e32 v35, v0
	v_mov_b32_e32 v36, v0
	v_mov_b32_e32 v37, v0
	v_mov_b32_e32 v38, v0
	v_mov_b32_e32 v39, v0
	v_mov_b32_e32 v40, v0
	v_mov_b32_e32 v41, v0
	v_mov_b32_e32 v42, v0
	v_mov_b32_e32 v43, v0
	v_mov_b32_e32 v44, v0
	v_mov_b32_e32 v45, v0
	v_mov_b32_e32 v46, v0
	v_mov_b32_e32 v47, v0
	v_mov_b32_e32 v48, v0
	v_mov_b32_e32 v49, v0
	v_mov_b32_e32 v50, v0
	v_mov_b32_e32 v51, v0
	v_mov_b32_e32 v52, v0
	v_mov_b32_e32 v53, v0
	v_mov_b32_e32 v54, v0
	v_mov_b32_e32 v55, v0
	v_mov_b32_e32 v56, v0
	v_mov_b32_e32 v57, v0
	v_mov_b32_e32 v58, v0
	v_mov_b32_e32 v59, v0
	v_mov_b32_e32 v60, v0
	v_mov_b32_e32 v61, v0
	v_mov_b32_e32 v62, v0
	v_mov_b32_e32 v63, v0
	s_waitcnt vmcnt(12)
	ds_write_b128 v173, v[80:83] offset:18432
	s_waitcnt vmcnt(11)
	ds_write_b128 v173, v[88:91] offset:23040
	s_waitcnt vmcnt(10)
	ds_write_b128 v173, v[96:99] offset:27648
	s_waitcnt vmcnt(9)
	ds_write_b128 v173, v[104:107] offset:32256
	ds_write_b128 v173, v[64:67]
	ds_write_b128 v173, v[68:71] offset:4608
	ds_write_b128 v173, v[72:75] offset:9216
	s_waitcnt vmcnt(8)
	ds_write_b128 v173, v[76:79] offset:13824
	s_waitcnt lgkmcnt(0)
	s_barrier
	v_lshl_add_u64 v[162:163], v[146:147], 0, v[140:141]
	v_lshl_add_u64 v[164:165], v[144:145], 0, v[140:141]
	v_add_co_u32_e32 v162, vcc, 0x270e0000, v162
	s_nop 1
	v_addc_co_u32_e32 v163, vcc, 0, v163, vcc
	v_add_co_u32_e32 v164, vcc, 0x3260000, v164
	s_nop 1
	v_addc_co_u32_e32 v165, vcc, 0, v165, vcc
	s_nop 0
	v_readfirstlane_b32 s30, v162
	v_readfirstlane_b32 s31, v163
	v_readfirstlane_b32 s34, v164
	v_readfirstlane_b32 s35, v165
	s_nop 1
	v_subrev_u32_e32 v156, s30, v162
	v_subrev_u32_e32 v160, s34, v164
	v_add_u32_e32 v157, 0x20000, v156
	v_add_u32_e32 v158, 0x40000, v156
	v_add_u32_e32 v159, 0x60000, v156
	v_add_u32_e32 v161, 0x20000, v160
	v_add_u32_e32 v170, 0x40000, v160
	v_add_u32_e32 v171, 0x60000, v160
	ds_read_b128 v[162:165], v136
	ds_read_b128 v[166:169], v136 offset:4608
	ds_read_b128 v[174:177], v131 offset:18432
	ds_read_b128 v[206:209], v131 offset:23040
; template <class LA>
; DI void gemm_tile(const LA& la, int m0, const u16* __restrict__ Bm, long ldb, int K, f32x16 (&acc)[2][2], char* lds, int tid) {
;     ...
;   const int arow = (wm * 64 + (lane & 31)) * 144 + (lane >> 5) * 16;
;   const int brow = 18432 + (wn * 64 + (lane & 31)) * 144 + (lane >> 5) * 16;
;   char* lds0 = lds;
;   char* lds1 = lds + 36864;
;   __syncthreads();
;   GT_LOAD(p, 0)
;   if (nk > 1) { GT_LOAD(q, 64) }
;   GT_STORE(p, lds0)
;   __syncthreads();
; #pragma unroll 1
;   for (int kt = 0; kt < nk; kt += 2) {
;     if (kt + 2 < nk) { GT_LOAD(p, (kt + 2) * 64) }
;     GT_COMPUTE(lds0)
;     if (kt + 1 < nk) { GT_STORE(q, lds1) }
;     __syncthreads();
;     if (kt + 1 >= nk) break;
;     if (kt + 3 < nk) { GT_LOAD(q, (kt + 3) * 64) }
;     GT_COMPUTE(lds1)
;     if (kt + 2 < nk) { GT_STORE(p, lds0) }
;     __syncthreads();
;   }
.Lp6n_loop:
	ds_read_b128 v[210:213], v136 offset:32
	ds_read_b128 v[214:217], v136 offset:4640
	ds_read_b128 v[218:221], v131 offset:18464
	ds_read_b128 v[222:225], v131 offset:23072
	s_waitcnt lgkmcnt(4)
	v_mfma_f32_32x32x16_bf16 v[48:63], v[162:165], v[174:177], v[48:63]
	global_load_dwordx4 v[64:67], v156, s[30:31] offset:256
	v_mfma_f32_32x32x16_bf16 v[32:47], v[162:165], v[206:209], v[32:47]
	global_load_dwordx4 v[68:71], v157, s[30:31] offset:256
	v_mfma_f32_32x32x16_bf16 v[16:31], v[166:169], v[174:177], v[16:31]
	global_load_dwordx4 v[72:75], v158, s[30:31] offset:256
	ds_read_b128 v[226:229], v136 offset:64
	ds_read_b128 v[230:233], v136 offset:4672
	v_mfma_f32_32x32x16_bf16 v[0:15], v[166:169], v[206:209], v[0:15]
	global_load_dwordx4 v[76:79], v159, s[30:31] offset:256
	ds_read_b128 v[234:237], v131 offset:18496
	ds_read_b128 v[238:241], v131 offset:23104
	s_waitcnt lgkmcnt(4)
	v_mfma_f32_32x32x16_bf16 v[48:63], v[210:213], v[218:221], v[48:63]
	global_load_dwordx4 v[80:83], v160, s[34:35] offset:256
	v_mfma_f32_32x32x16_bf16 v[32:47], v[210:213], v[222:225], v[32:47]
	global_load_dwordx4 v[88:91], v161, s[34:35] offset:256
	v_mfma_f32_32x32x16_bf16 v[16:31], v[214:217], v[218:221], v[16:31]
	global_load_dwordx4 v[96:99], v170, s[34:35] offset:256
	ds_read_b128 v[242:245], v136 offset:96
	ds_read_b128 v[246:249], v136 offset:4704
	v_mfma_f32_32x32x16_bf16 v[0:15], v[214:217], v[222:225], v[0:15]
	global_load_dwordx4 v[104:107], v171, s[34:35] offset:256
	ds_read_b128 v[250:253], v131 offset:18528
	ds_read_b128 v[144:147], v131 offset:23136
	s_waitcnt vmcnt(8) lgkmcnt(4)
	v_mfma_f32_32x32x16_bf16 v[48:63], v[226:229], v[234:237], v[48:63]
	ds_write_b128 v173, v[84:87] offset:36864
	ds_write_b128 v173, v[92:95] offset:41472
	ds_write_b128 v173, v[100:103] offset:46080
	v_mfma_f32_32x32x16_bf16 v[32:47], v[226:229], v[238:241], v[32:47]
	ds_write_b128 v173, v[108:111] offset:50688
	ds_write_b128 v173, v[112:115] offset:55296
	ds_write_b128 v173, v[116:119] offset:59904
	v_mfma_f32_32x32x16_bf16 v[16:31], v[230:233], v[234:237], v[16:31]
	ds_write_b128 v173, v[120:123] offset:64512
	ds_write_b128 v172, v[124:127] offset:13824
	v_mfma_f32_32x32x16_bf16 v[0:15], v[230:233], v[238:241], v[0:15]
	s_waitcnt lgkmcnt(0)
	s_barrier
	v_mfma_f32_32x32x16_bf16 v[48:63], v[242:245], v[250:253], v[48:63]
	ds_read_b128 v[162:165], v136 offset:36864
	ds_read_b128 v[166:169], v136 offset:41472
	v_mfma_f32_32x32x16_bf16 v[32:47], v[242:245], v[144:147], v[32:47]
	ds_read_b128 v[174:177], v131 offset:55296
	ds_read_b128 v[206:209], v131 offset:59904
	v_mfma_f32_32x32x16_bf16 v[16:31], v[246:249], v[250:253], v[16:31]
	v_mfma_f32_32x32x16_bf16 v[0:15], v[246:249], v[144:147], v[0:15]
	ds_read_b128 v[210:213], v136 offset:36896
	ds_read_b128 v[214:217], v136 offset:41504
	ds_read_b128 v[218:221], v131 offset:55328
	ds_read_b128 v[222:225], v131 offset:59936
	s_waitcnt lgkmcnt(4)
	v_mfma_f32_32x32x16_bf16 v[48:63], v[162:165], v[174:177], v[48:63]
	global_load_dwordx4 v[84:87], v156, s[30:31] offset:384
	v_mfma_f32_32x32x16_bf16 v[32:47], v[162:165], v[206:209], v[32:47]
	global_load_dwordx4 v[92:95], v157, s[30:31] offset:384
	v_mfma_f32_32x32x16_bf16 v[16:31], v[166:169], v[174:177], v[16:31]
	global_load_dwordx4 v[100:103], v158, s[30:31] offset:384
	ds_read_b128 v[226:229], v136 offset:36928
	ds_read_b128 v[230:233], v136 offset:41536
	v_mfma_f32_32x32x16_bf16 v[0:15], v[166:169], v[206:209], v[0:15]
	global_load_dwordx4 v[108:111], v159, s[30:31] offset:384
	ds_read_b128 v[234:237], v131 offset:55360
	ds_read_b128 v[238:241], v131 offset:59968
	s_waitcnt lgkmcnt(4)
	v_mfma_f32_32x32x16_bf16 v[48:63], v[210:213], v[218:221], v[48:63]
	global_load_dwordx4 v[112:115], v160, s[34:35] offset:384
	v_mfma_f32_32x32x16_bf16 v[32:47], v[210:213], v[222:225], v[32:47]
	global_load_dwordx4 v[116:119], v161, s[34:35] offset:384
	v_mfma_f32_32x32x16_bf16 v[16:31], v[214:217], v[218:221], v[16:31]
	global_load_dwordx4 v[120:123], v170, s[34:35] offset:384
	ds_read_b128 v[242:245], v136 offset:36960
	ds_read_b128 v[246:249], v136 offset:41568
	v_mfma_f32_32x32x16_bf16 v[0:15], v[214:217], v[222:225], v[0:15]
	global_load_dwordx4 v[124:127], v171, s[34:35] offset:384
	ds_read_b128 v[250:253], v131 offset:55392
	ds_read_b128 v[144:147], v131 offset:60000
	s_waitcnt vmcnt(8) lgkmcnt(4)
	v_mfma_f32_32x32x16_bf16 v[48:63], v[226:229], v[234:237], v[48:63]
	ds_write_b128 v173, v[64:67]
	ds_write_b128 v173, v[68:71] offset:4608
	ds_write_b128 v173, v[72:75] offset:9216
	v_mfma_f32_32x32x16_bf16 v[32:47], v[226:229], v[238:241], v[32:47]
	ds_write_b128 v173, v[76:79] offset:13824
	ds_write_b128 v173, v[80:83] offset:18432
	ds_write_b128 v173, v[88:91] offset:23040
	v_mfma_f32_32x32x16_bf16 v[16:31], v[230:233], v[234:237], v[16:31]
	ds_write_b128 v173, v[96:99] offset:27648
	ds_write_b128 v173, v[104:107] offset:32256
	v_mfma_f32_32x32x16_bf16 v[0:15], v[230:233], v[238:241], v[0:15]
	s_waitcnt lgkmcnt(0)
	s_barrier
	v_mfma_f32_32x32x16_bf16 v[48:63], v[242:245], v[250:253], v[48:63]
	ds_read_b128 v[162:165], v136
	ds_read_b128 v[166:169], v136 offset:4608
	v_mfma_f32_32x32x16_bf16 v[32:47], v[242:245], v[144:147], v[32:47]
	ds_read_b128 v[174:177], v131 offset:18432
	ds_read_b128 v[206:209], v131 offset:23040
	v_mfma_f32_32x32x16_bf16 v[16:31], v[246:249], v[250:253], v[16:31]
	v_mfma_f32_32x32x16_bf16 v[0:15], v[246:249], v[144:147], v[0:15]
	s_add_u32 s30, s30, 0x100
	s_addc_u32 s31, s31, 0
	s_add_u32 s34, s34, 0x100
	s_addc_u32 s35, s35, 0
	s_add_i32 s7, s7, 2
	s_cmp_lt_u32 s7, 30
	s_cbranch_scc1 .Lp6n_loop
	s_branch .LBB0_302

; #define MFMA32(a, b, c) __builtin_amdgcn_mfma_f32_32x32x16_bf16((a), (b), (c), 0, 0, 0)
; template <int MODE>
; DI void attn_item(const u16* __restrict__ Qp, const u16* __restrict__ Kp, const u16* __restrict__ VTp, int q0,
;                   int kt_lo, int kt_hi, u16* __restrict__ Op, int os, float* __restrict__ lsep, int ls, char* lds, int tid) {
;     ...
; #pragma unroll
;     for (int s4 = 0; s4 < NS4; s4++) {
;       const int mt = s4 >> 1, r0 = (s4 & 1) * 8;
;       uint4 pw;
;       pw.x = pack2(st[mt][r0 + 0], st[mt][r0 + 1]);
;       pw.y = pack2(st[mt][r0 + 2], st[mt][r0 + 3]);
;       pw.z = pack2(st[mt][r0 + 4], st[mt][r0 + 5]);
;       pw.w = pack2(st[mt][r0 + 6], st[mt][r0 + 7]);
;       const bf16x8 pb = __builtin_bit_cast(bf16x8, pw);
; #pragma unroll
;       for (int dt = 0; dt < 4; dt++) {
;         const char* vr = Vs + (dt * 32 + c) * VROW + (16 * s4 + 4 * h) * 2;
;         const bf16x4 lo = *(const bf16x4*)(vr);
;         const bf16x4 hi = *(const bf16x4*)(vr + 16);
;         const bf16x8 vf = __builtin_shufflevector(lo, hi, 0, 1, 2, 3, 4, 5, 6, 7);
;         ot[dt] = MFMA32(vf, pb, ot[dt]);
;       }
;     }
;     if (MODE == 1) {
;       if (__syncthreads_and(R < -100.f)) break;
;     }
;     if (PF) {
;       if (it + 1 < ntiles) { PF_STORE((it + 1) & 1) }
;       __syncthreads();
;     }
;   }
.Lp4_pv:
	v_cvt_pk_bf16_f32 v67, v225, v226
	s_add_i32 s42, s42, 1
	s_andn2_b64 vcc, exec, s[12:13]
	s_waitcnt lgkmcnt(4)
	s_nop 0
	v_mfma_f32_32x32x16_bf16 v[48:63], v[236:239], v[64:67], v[48:63]
	ds_read_b64 v[236:237], v252 offset:17952
	ds_read_b64 v[238:239], v252 offset:17968
	v_mfma_f32_32x32x16_bf16 v[32:47], v[240:243], v[64:67], v[32:47]
	ds_read_b64 v[240:241], v252 offset:20512
	ds_read_b64 v[242:243], v252 offset:20528
	v_mfma_f32_32x32x16_bf16 v[16:31], v[244:247], v[64:67], v[16:31]
	v_mfma_f32_32x32x16_bf16 v[0:15], v[248:251], v[64:67], v[0:15]
	v_cvt_pk_bf16_f32 v64, v227, v228
	v_cvt_pk_bf16_f32 v65, v229, v230
	v_cvt_pk_bf16_f32 v66, v231, v232
	v_cvt_pk_bf16_f32 v67, v233, v234
	s_waitcnt lgkmcnt(4)
	s_nop 0
	v_mfma_f32_32x32x16_bf16 v[32:47], v[74:77], v[64:67], v[32:47]
	s_waitcnt lgkmcnt(2)
	v_mfma_f32_32x32x16_bf16 v[16:31], v[236:239], v[64:67], v[16:31]
	v_mfma_f32_32x32x16_bf16 v[48:63], v[70:73], v[64:67], v[48:63]
	s_waitcnt lgkmcnt(0)
	v_mfma_f32_32x32x16_bf16 v[0:15], v[240:243], v[64:67], v[0:15]
	s_cbranch_vccnz .LBB0_473
	s_bitcmp1_b32 s42, 0
	s_cselect_b32 s11, 0x5a00, 0
	v_add3_u32 v64, s11, v209, v174
	s_waitcnt vmcnt(4)
	ds_write_b128 v64, v[128:131]
	s_waitcnt vmcnt(3)
	ds_write_b128 v64, v[132:135] offset:128
	s_waitcnt vmcnt(2)
	ds_write_b128 v64, v[136:139] offset:256
	v_add3_u32 v64, s11, v177, v175
	s_waitcnt vmcnt(1)
	ds_write_b128 v64, v[140:143] offset:12800
	s_waitcnt vmcnt(0)
	ds_write_b128 v64, v[144:147] offset:17920
